# A epilogue: the 16 sub-LN gain vector loads issued together up front into dead registers with one wait, instead of one load per wait each also draining the previous output store
# baseline (speedup 1.0000x reference)
; DI float swapsum(float m) { auto rr = __builtin_amdgcn_permlane32_swap(__float_as_uint(m), __float_as_uint(m), false, false); return __uint_as_float(rr[0]) + __uint_as_float(rr[1]); }
; template <int KIND> DI void attn_unit(const Params& P, int b, int h, int qb, char* shm, float lam, bool dry = false) {
;     ...
;         if (m == 0) {
;             float ss = 0.f;
; #pragma unroll
;             for (int db = 0; db < NDB; ++db)
; #pragma unroll
;                 for (int r = 0; r < 16; ++r) { const float d = o[db][r] * rl - lam * comb[(db * 16 + r) * 64]; o[db][r] = d; ss += d * d; }
;             ss = swapsum(ss);
.LBB0_414:
	s_waitcnt vmcnt(0) lgkmcnt(0)
	s_barrier
	s_cmpk_gt_u32 s12, 0xff
	s_cbranch_scc1 .LBB0_317
	ds_read2st64_b32 v[102:103], v4 offset1:1
	ds_read2st64_b32 v[98:99], v4 offset0:2 offset1:3
	ds_read2st64_b32 v[96:97], v4 offset0:4 offset1:5
	ds_read2st64_b32 v[92:93], v4 offset0:6 offset1:7
	ds_read2st64_b32 v[120:121], v4 offset0:8 offset1:9
	ds_read2st64_b32 v[122:123], v4 offset0:10 offset1:11
	ds_read2st64_b32 v[124:125], v4 offset0:12 offset1:13
	ds_read2st64_b32 v[126:127], v4 offset0:14 offset1:15
	ds_read2st64_b32 v[128:129], v4 offset0:16 offset1:17
	ds_read2st64_b32 v[130:131], v4 offset0:18 offset1:19
	ds_read2st64_b32 v[132:133], v4 offset0:20 offset1:21
	ds_read2st64_b32 v[134:135], v4 offset0:22 offset1:23
	ds_read2st64_b32 v[118:119], v4 offset0:24 offset1:25
	ds_read2st64_b32 v[136:137], v4 offset0:26 offset1:27
	ds_read2st64_b32 v[138:139], v4 offset0:28 offset1:29
	ds_read2st64_b32 v[140:141], v4 offset0:30 offset1:31
	ds_read2st64_b32 v[110:111], v4 offset0:32 offset1:33
	ds_read2st64_b32 v[112:113], v4 offset0:34 offset1:35
	ds_read2st64_b32 v[114:115], v4 offset0:36 offset1:37
	ds_read2st64_b32 v[116:117], v4 offset0:38 offset1:39
	ds_read2st64_b32 v[100:101], v4 offset0:40 offset1:41
	ds_read2st64_b32 v[104:105], v4 offset0:42 offset1:43
	ds_read2st64_b32 v[106:107], v4 offset0:44 offset1:45
	ds_read2st64_b32 v[108:109], v4 offset0:46 offset1:47
	ds_read2st64_b32 v[88:89], v4 offset0:48 offset1:49
	ds_read2st64_b32 v[90:91], v4 offset0:50 offset1:51
	ds_read2st64_b32 v[94:95], v4 offset0:52 offset1:53
	ds_read2st64_b32 v[18:19], v4 offset0:54 offset1:55
	ds_read2st64_b32 v[84:85], v4 offset0:56 offset1:57
	ds_read2st64_b32 v[86:87], v4 offset0:58 offset1:59
	ds_read2st64_b32 v[14:15], v4 offset0:60 offset1:61
	ds_read2st64_b32 v[4:5], v4 offset0:62 offset1:63
	s_lshl_b32 s20, s2, 1
	v_readlane_b32 s0, v255, 23
	v_lshl_add_u64 v[0:1], v[0:1], 0, s[20:21]
	v_lshlrev_b32_e32 v3, 2, v3
	s_waitcnt lgkmcnt(0)
	v_pk_mul_f32 v[4:5], v[188:189], v[4:5]
	v_readlane_b32 s1, v255, 24
	v_pk_fma_f32 v[12:13], v[34:35], v[16:17], v[4:5] op_sel_hi:[1,0,1] neg_lo:[0,0,1] neg_hi:[0,0,1]
	v_pk_mul_f32 v[34:35], v[188:189], v[92:93]
	v_lshlrev_b32_e32 v4, 1, v198
	v_pk_fma_f32 v[92:93], v[74:75], v[16:17], v[34:35] op_sel_hi:[1,0,1] neg_lo:[0,0,1] neg_hi:[0,0,1]
	v_pk_mul_f32 v[34:35], v[188:189], v[96:97]
	v_mov_b32_e32 v5, v2
	v_pk_fma_f32 v[96:97], v[72:73], v[16:17], v[34:35] op_sel_hi:[1,0,1] neg_lo:[0,0,1] neg_hi:[0,0,1]
	v_pk_mul_f32 v[34:35], v[188:189], v[98:99]
	v_lshl_add_u64 v[0:1], v[0:1], 0, v[4:5]
	v_pk_fma_f32 v[98:99], v[70:71], v[16:17], v[34:35] op_sel_hi:[1,0,1] neg_lo:[0,0,1] neg_hi:[0,0,1]
	v_pk_mul_f32 v[34:35], v[188:189], v[102:103]
	global_load_dwordx4 v[148:151], v3, s[0:1]
	global_load_dwordx4 v[152:155], v3, s[0:1] offset:32
	global_load_dwordx4 v[156:159], v3, s[0:1] offset:64
	global_load_dwordx4 v[160:163], v3, s[0:1] offset:96
	global_load_dwordx4 v[164:167], v3, s[0:1] offset:128
	global_load_dwordx4 v[168:171], v3, s[0:1] offset:160
	global_load_dwordx4 v[172:175], v3, s[0:1] offset:192
	global_load_dwordx4 v[176:179], v3, s[0:1] offset:224
	global_load_dwordx4 v[180:183], v3, s[0:1] offset:256
	global_load_dwordx4 v[184:187], v3, s[0:1] offset:288
	global_load_dwordx4 v[208:211], v3, s[0:1] offset:320
	global_load_dwordx4 v[220:223], v3, s[0:1] offset:352
	global_load_dwordx4 v[224:227], v3, s[0:1] offset:384
	global_load_dwordx4 v[228:231], v3, s[0:1] offset:416
	global_load_dwordx4 v[232:235], v3, s[0:1] offset:448
	global_load_dwordx4 v[190:193], v3, s[0:1] offset:480
	v_pk_fma_f32 v[102:103], v[68:69], v[16:17], v[34:35] op_sel_hi:[1,0,1] neg_lo:[0,0,1] neg_hi:[0,0,1]
	v_mul_f32_e32 v68, v99, v99
	v_mul_f32_e32 v34, v103, v103
	v_pk_fma_f32 v[34:35], v[102:103], v[102:103], v[34:35] op_sel_hi:[1,1,0]
	v_pk_mul_f32 v[18:19], v[188:189], v[18:19]
	v_pk_fma_f32 v[34:35], v[98:99], v[98:99], v[34:35]
	v_pk_fma_f32 v[18:19], v[26:27], v[16:17], v[18:19] op_sel_hi:[1,0,1] neg_lo:[0,0,1] neg_hi:[0,0,1]
	v_pk_add_f32 v[34:35], v[34:35], v[68:69] op_sel_hi:[1,0]
	v_mul_f32_e32 v68, v97, v97
	v_pk_fma_f32 v[34:35], v[96:97], v[96:97], v[34:35]
	v_pk_mul_f32 v[26:27], v[188:189], v[94:95]
	v_pk_add_f32 v[34:35], v[34:35], v[68:69] op_sel_hi:[1,0]
	v_mul_f32_e32 v68, v93, v93
	v_pk_fma_f32 v[34:35], v[92:93], v[92:93], v[34:35]
	v_pk_fma_f32 v[24:25], v[24:25], v[16:17], v[26:27] op_sel_hi:[1,0,1] neg_lo:[0,0,1] neg_hi:[0,0,1]
	v_pk_add_f32 v[34:35], v[34:35], v[68:69] op_sel_hi:[1,0]
	v_pk_mul_f32 v[68:69], v[188:189], v[126:127]
	v_pk_mul_f32 v[26:27], v[188:189], v[90:91]
	v_pk_fma_f32 v[72:73], v[82:83], v[16:17], v[68:69] op_sel_hi:[1,0,1] neg_lo:[0,0,1] neg_hi:[0,0,1]
	v_pk_mul_f32 v[68:69], v[188:189], v[124:125]
	v_pk_fma_f32 v[26:27], v[22:23], v[16:17], v[26:27] op_sel_hi:[1,0,1] neg_lo:[0,0,1] neg_hi:[0,0,1]
	v_pk_fma_f32 v[74:75], v[80:81], v[16:17], v[68:69] op_sel_hi:[1,0,1] neg_lo:[0,0,1] neg_hi:[0,0,1]
	v_pk_mul_f32 v[68:69], v[188:189], v[122:123]
	v_pk_mul_f32 v[22:23], v[188:189], v[88:89]
	v_pk_fma_f32 v[80:81], v[78:79], v[16:17], v[68:69] op_sel_hi:[1,0,1] neg_lo:[0,0,1] neg_hi:[0,0,1]
	v_pk_mul_f32 v[68:69], v[188:189], v[120:121]
	v_pk_mul_f32 v[14:15], v[188:189], v[14:15]
	v_pk_fma_f32 v[82:83], v[76:77], v[16:17], v[68:69] op_sel_hi:[1,0,1] neg_lo:[0,0,1] neg_hi:[0,0,1]
	v_pk_fma_f32 v[14:15], v[32:33], v[16:17], v[14:15] op_sel_hi:[1,0,1] neg_lo:[0,0,1] neg_hi:[0,0,1]
	v_pk_fma_f32 v[34:35], v[82:83], v[82:83], v[34:35]
	v_mul_f32_e32 v68, v83, v83
	v_pk_add_f32 v[34:35], v[34:35], v[68:69] op_sel_hi:[1,0]
	v_mul_f32_e32 v68, v81, v81
	v_pk_fma_f32 v[34:35], v[80:81], v[80:81], v[34:35]
; DI unsigned cvtpk(float lo, float hi) { f32x2_t v = {lo, hi}; bf16x2_t b = __builtin_convertvector(v, bf16x2_t); return __builtin_bit_cast(unsigned, b); }
; DI float swapsum(float m) { auto rr = __builtin_amdgcn_permlane32_swap(__float_as_uint(m), __float_as_uint(m), false, false); return __uint_as_float(rr[0]) + __uint_as_float(rr[1]); }
; template <int KIND> DI void attn_unit(const Params& P, int b, int h, int qb, char* shm, float lam, bool dry = false) {
;     ...
;                 for (int r = 0; r < 16; ++r) { const float d = o[db][r] * rl - lam * comb[(db * 16 + r) * 64]; o[db][r] = d; ss += d * d; }
;             ss = swapsum(ss);
;             const float sc = __builtin_amdgcn_rsqf(ss * (1.0f / 128.0f) + RMS_EPS) * (1.0f - P.lam_init);
; #pragma unroll
;             for (int db = 0; db < NDB; ++db)
; #pragma unroll
;                 for (int g = 0; g < 4; g += 2) { u32x2 wp[2];
; #pragma unroll
;                     for (int e = 0; e < 2; ++e) { const f32x4 sg = *(const f32x4*)(P.subg + db * 32 + 8 * (g + e) + 4 * hi); const int r = 4 * (g + e);
;                         wp[e].x = cvtpk(o[db][r] * sc * sg[0], o[db][r + 1] * sc * sg[1]); wp[e].y = cvtpk(o[db][r + 2] * sc * sg[2], o[db][r + 3] * sc * sg[3]); }
	s_nop 0
	v_pk_add_f32 v[34:35], v[34:35], v[68:69] op_sel_hi:[1,0]
	v_mul_f32_e32 v68, v75, v75
	v_pk_fma_f32 v[34:35], v[74:75], v[74:75], v[34:35]
	s_nop 0
	v_pk_add_f32 v[34:35], v[34:35], v[68:69] op_sel_hi:[1,0]
	v_mul_f32_e32 v68, v73, v73
	v_pk_fma_f32 v[34:35], v[72:73], v[72:73], v[34:35]
	s_nop 0
	v_pk_add_f32 v[34:35], v[34:35], v[68:69] op_sel_hi:[1,0]
	v_pk_mul_f32 v[68:69], v[188:189], v[134:135]
	s_nop 0
	v_pk_fma_f32 v[68:69], v[58:59], v[16:17], v[68:69] op_sel_hi:[1,0,1] neg_lo:[0,0,1] neg_hi:[0,0,1]
	v_pk_mul_f32 v[58:59], v[188:189], v[132:133]
	s_nop 0
	v_pk_fma_f32 v[70:71], v[56:57], v[16:17], v[58:59] op_sel_hi:[1,0,1] neg_lo:[0,0,1] neg_hi:[0,0,1]
	v_pk_mul_f32 v[56:57], v[188:189], v[130:131]
	s_nop 0
	v_pk_fma_f32 v[76:77], v[54:55], v[16:17], v[56:57] op_sel_hi:[1,0,1] neg_lo:[0,0,1] neg_hi:[0,0,1]
	v_pk_mul_f32 v[54:55], v[188:189], v[128:129]
	s_nop 0
	v_pk_fma_f32 v[78:79], v[52:53], v[16:17], v[54:55] op_sel_hi:[1,0,1] neg_lo:[0,0,1] neg_hi:[0,0,1]
	s_nop 0
	v_pk_fma_f32 v[34:35], v[78:79], v[78:79], v[34:35]
	v_mul_f32_e32 v52, v79, v79
	v_pk_add_f32 v[34:35], v[34:35], v[52:53] op_sel_hi:[1,0]
	v_mul_f32_e32 v52, v77, v77
	v_pk_fma_f32 v[34:35], v[76:77], v[76:77], v[34:35]
	s_nop 0
	v_pk_add_f32 v[34:35], v[34:35], v[52:53] op_sel_hi:[1,0]
	v_mul_f32_e32 v52, v71, v71
	v_pk_fma_f32 v[34:35], v[70:71], v[70:71], v[34:35]
	s_nop 0
	v_pk_add_f32 v[34:35], v[34:35], v[52:53] op_sel_hi:[1,0]
	v_mul_f32_e32 v52, v69, v69
	v_pk_fma_f32 v[34:35], v[68:69], v[68:69], v[34:35]
	s_nop 0
	v_pk_add_f32 v[34:35], v[34:35], v[52:53] op_sel_hi:[1,0]
	v_pk_mul_f32 v[52:53], v[188:189], v[140:141]
	s_nop 0
	v_pk_fma_f32 v[54:55], v[66:67], v[16:17], v[52:53] op_sel_hi:[1,0,1] neg_lo:[0,0,1] neg_hi:[0,0,1]
	v_pk_mul_f32 v[52:53], v[188:189], v[138:139]
	s_nop 0
	v_pk_fma_f32 v[64:65], v[64:65], v[16:17], v[52:53] op_sel_hi:[1,0,1] neg_lo:[0,0,1] neg_hi:[0,0,1]
	v_pk_mul_f32 v[52:53], v[188:189], v[136:137]
	s_nop 0
	v_pk_fma_f32 v[62:63], v[62:63], v[16:17], v[52:53] op_sel_hi:[1,0,1] neg_lo:[0,0,1] neg_hi:[0,0,1]
	v_pk_mul_f32 v[52:53], v[188:189], v[118:119]
	s_nop 0
	v_pk_fma_f32 v[60:61], v[60:61], v[16:17], v[52:53] op_sel_hi:[1,0,1] neg_lo:[0,0,1] neg_hi:[0,0,1]
	s_nop 0
	v_pk_fma_f32 v[34:35], v[60:61], v[60:61], v[34:35]
	v_mul_f32_e32 v52, v61, v61
	v_pk_add_f32 v[34:35], v[34:35], v[52:53] op_sel_hi:[1,0]
	v_mul_f32_e32 v52, v63, v63
	v_pk_fma_f32 v[34:35], v[62:63], v[62:63], v[34:35]
	s_nop 0
	v_pk_add_f32 v[34:35], v[34:35], v[52:53] op_sel_hi:[1,0]
	v_mul_f32_e32 v52, v65, v65
	v_pk_fma_f32 v[34:35], v[64:65], v[64:65], v[34:35]
	s_nop 0
	v_pk_add_f32 v[34:35], v[34:35], v[52:53] op_sel_hi:[1,0]
	v_mul_f32_e32 v52, v55, v55
	v_pk_fma_f32 v[34:35], v[54:55], v[54:55], v[34:35]
	s_nop 0
	v_pk_add_f32 v[34:35], v[34:35], v[52:53] op_sel_hi:[1,0]
	v_pk_mul_f32 v[52:53], v[188:189], v[116:117]
	s_nop 0
	v_pk_fma_f32 v[42:43], v[42:43], v[16:17], v[52:53] op_sel_hi:[1,0,1] neg_lo:[0,0,1] neg_hi:[0,0,1]
	v_pk_mul_f32 v[52:53], v[188:189], v[114:115]
	s_nop 0
	v_pk_fma_f32 v[52:53], v[40:41], v[16:17], v[52:53] op_sel_hi:[1,0,1] neg_lo:[0,0,1] neg_hi:[0,0,1]
	v_pk_mul_f32 v[40:41], v[188:189], v[112:113]
	s_nop 0
	v_pk_fma_f32 v[56:57], v[38:39], v[16:17], v[40:41] op_sel_hi:[1,0,1] neg_lo:[0,0,1] neg_hi:[0,0,1]
	v_pk_mul_f32 v[38:39], v[188:189], v[110:111]
	v_pk_mul_f32 v[40:41], v[188:189], v[104:105]
	v_pk_fma_f32 v[58:59], v[36:37], v[16:17], v[38:39] op_sel_hi:[1,0,1] neg_lo:[0,0,1] neg_hi:[0,0,1]
	v_pk_fma_f32 v[40:41], v[46:47], v[16:17], v[40:41] op_sel_hi:[1,0,1] neg_lo:[0,0,1] neg_hi:[0,0,1]
	v_pk_fma_f32 v[34:35], v[58:59], v[58:59], v[34:35]
	v_mul_f32_e32 v36, v59, v59
	v_pk_add_f32 v[34:35], v[34:35], v[36:37] op_sel_hi:[1,0]
	v_mul_f32_e32 v36, v57, v57
	v_pk_fma_f32 v[34:35], v[56:57], v[56:57], v[34:35]
	v_pk_mul_f32 v[46:47], v[188:189], v[100:101]
	v_pk_add_f32 v[34:35], v[34:35], v[36:37] op_sel_hi:[1,0]
	v_mul_f32_e32 v36, v53, v53
	v_pk_fma_f32 v[34:35], v[52:53], v[52:53], v[34:35]
	v_pk_fma_f32 v[44:45], v[44:45], v[16:17], v[46:47] op_sel_hi:[1,0,1] neg_lo:[0,0,1] neg_hi:[0,0,1]
	v_pk_add_f32 v[34:35], v[34:35], v[36:37] op_sel_hi:[1,0]
	v_mul_f32_e32 v36, v43, v43
	v_pk_fma_f32 v[34:35], v[42:43], v[42:43], v[34:35]
	v_mul_f32_e32 v46, v45, v45
	v_pk_add_f32 v[36:37], v[34:35], v[36:37] op_sel_hi:[1,0]
	v_pk_mul_f32 v[38:39], v[188:189], v[106:107]
	v_pk_fma_f32 v[36:37], v[44:45], v[44:45], v[36:37]
	v_pk_fma_f32 v[38:39], v[48:49], v[16:17], v[38:39] op_sel_hi:[1,0,1] neg_lo:[0,0,1] neg_hi:[0,0,1]
	v_pk_add_f32 v[36:37], v[36:37], v[46:47] op_sel_hi:[1,0]
	v_mul_f32_e32 v46, v41, v41
	v_pk_fma_f32 v[36:37], v[40:41], v[40:41], v[36:37]
	v_pk_mul_f32 v[34:35], v[188:189], v[108:109]
	v_pk_add_f32 v[36:37], v[36:37], v[46:47] op_sel_hi:[1,0]
	v_mul_f32_e32 v46, v39, v39
	v_pk_fma_f32 v[36:37], v[38:39], v[38:39], v[36:37]
	v_pk_fma_f32 v[34:35], v[50:51], v[16:17], v[34:35] op_sel_hi:[1,0,1] neg_lo:[0,0,1] neg_hi:[0,0,1]
	v_pk_add_f32 v[36:37], v[36:37], v[46:47] op_sel_hi:[1,0]
	v_mul_f32_e32 v46, v35, v35
	v_pk_fma_f32 v[36:37], v[34:35], v[34:35], v[36:37]
	s_nop 0
	v_pk_add_f32 v[46:47], v[36:37], v[46:47] op_sel_hi:[1,0]
	v_pk_fma_f32 v[36:37], v[20:21], v[16:17], v[22:23] op_sel_hi:[1,0,1] neg_lo:[0,0,1] neg_hi:[0,0,1]
	s_nop 0
	v_pk_fma_f32 v[20:21], v[36:37], v[36:37], v[46:47]
	v_mul_f32_e32 v22, v37, v37
	v_pk_add_f32 v[20:21], v[20:21], v[22:23] op_sel_hi:[1,0]
	v_mul_f32_e32 v22, v27, v27
	v_pk_fma_f32 v[20:21], v[26:27], v[26:27], v[20:21]
	s_nop 0
	v_pk_add_f32 v[20:21], v[20:21], v[22:23] op_sel_hi:[1,0]
	v_mul_f32_e32 v22, v25, v25
	v_pk_fma_f32 v[20:21], v[24:25], v[24:25], v[20:21]
	s_nop 0
	v_pk_add_f32 v[20:21], v[20:21], v[22:23] op_sel_hi:[1,0]
	v_mul_f32_e32 v22, v19, v19
	v_pk_fma_f32 v[20:21], v[18:19], v[18:19], v[20:21]
	s_nop 0
	v_pk_add_f32 v[46:47], v[20:21], v[22:23] op_sel_hi:[1,0]
	v_pk_mul_f32 v[22:23], v[188:189], v[84:85]
	v_pk_mul_f32 v[20:21], v[188:189], v[86:87]
	v_pk_fma_f32 v[22:23], v[28:29], v[16:17], v[22:23] op_sel_hi:[1,0,1] neg_lo:[0,0,1] neg_hi:[0,0,1]
	v_pk_fma_f32 v[20:21], v[30:31], v[16:17], v[20:21] op_sel_hi:[1,0,1] neg_lo:[0,0,1] neg_hi:[0,0,1]
	v_pk_fma_f32 v[16:17], v[22:23], v[22:23], v[46:47]
	v_mul_f32_e32 v28, v23, v23
	v_pk_add_f32 v[16:17], v[16:17], v[28:29] op_sel_hi:[1,0]
	v_mul_f32_e32 v28, v21, v21
	v_pk_fma_f32 v[16:17], v[20:21], v[20:21], v[16:17]
	s_nop 0
	v_pk_add_f32 v[16:17], v[16:17], v[28:29] op_sel_hi:[1,0]
	v_mul_f32_e32 v28, v15, v15
	v_pk_fma_f32 v[16:17], v[14:15], v[14:15], v[16:17]
	s_nop 0
	v_pk_add_f32 v[16:17], v[16:17], v[28:29] op_sel_hi:[1,0]
	v_mul_f32_e32 v28, v13, v13
	v_pk_fma_f32 v[16:17], v[12:13], v[12:13], v[16:17]
	s_nop 0
	v_pk_add_f32 v[16:17], v[16:17], v[28:29] op_sel_hi:[1,0]
	s_nop 0
	v_mov_b32_e32 v17, v16
	s_nop 1
	v_permlane32_swap_b32_e32 v16, v17
	v_add_f32_e32 v16, v16, v17
	v_fmamk_f32 v16, v16, 0x3c000000, v237
	v_rsq_f32_e32 v16, v16
	s_nop 0
	v_mul_f32_e32 v16, v194, v16
	v_pk_mul_f32 v[28:29], v[102:103], v[16:17] op_sel_hi:[1,0]
	s_waitcnt vmcnt(0)
; DI unsigned cvtpk(float lo, float hi) { f32x2_t v = {lo, hi}; bf16x2_t b = __builtin_convertvector(v, bf16x2_t); return __builtin_bit_cast(unsigned, b); }
; template <int KIND> DI void attn_unit(const Params& P, int b, int h, int qb, char* shm, float lam, bool dry = false) {
;     ...
; #pragma unroll
;             for (int db = 0; db < NDB; ++db)
; #pragma unroll
;                 for (int g = 0; g < 4; g += 2) { u32x2 wp[2];
; #pragma unroll
;                     for (int e = 0; e < 2; ++e) { const f32x4 sg = *(const f32x4*)(P.subg + db * 32 + 8 * (g + e) + 4 * hi); const int r = 4 * (g + e);
;                         wp[e].x = cvtpk(o[db][r] * sc * sg[0], o[db][r + 1] * sc * sg[1]); wp[e].y = cvtpk(o[db][r + 2] * sc * sg[2], o[db][r + 3] * sc * sg[3]); }
;                     store_pair16(orow + db * 32 + 8 * g, hi, wp[0], wp[1], dry); }
	v_pk_mul_f32 v[8:9], v[148:149], v[28:29]
	v_pk_mul_f32 v[28:29], v[98:99], v[16:17] op_sel_hi:[1,0]
	v_cvt_pk_bf16_f32 v8, v8, v9
	v_pk_mul_f32 v[10:11], v[150:151], v[28:29]
	s_nop 0
	v_cvt_pk_bf16_f32 v9, v10, v11
	v_pk_mul_f32 v[10:11], v[96:97], v[16:17] op_sel_hi:[1,0]
	s_nop 0
	v_pk_mul_f32 v[4:5], v[152:153], v[10:11]
	s_nop 0
	v_cvt_pk_bf16_f32 v10, v4, v5
	v_pk_mul_f32 v[4:5], v[92:93], v[16:17] op_sel_hi:[1,0]
	s_nop 0
	v_permlane32_swap_b32_e32 v8, v10
	v_pk_mul_f32 v[4:5], v[154:155], v[4:5]
	s_nop 0
	v_cvt_pk_bf16_f32 v11, v4, v5
	s_nop 1
	v_permlane32_swap_b32_e32 v9, v11
	global_store_dwordx4 v[0:1], v[8:11], off
	s_nop 0
	s_nop 0
	v_pk_mul_f32 v[8:9], v[82:83], v[16:17] op_sel_hi:[1,0]
	v_pk_mul_f32 v[10:11], v[74:75], v[16:17] op_sel_hi:[1,0]
	s_nop 0
	v_pk_mul_f32 v[4:5], v[156:157], v[8:9]
	v_pk_mul_f32 v[8:9], v[80:81], v[16:17] op_sel_hi:[1,0]
	v_cvt_pk_bf16_f32 v4, v4, v5
	v_pk_mul_f32 v[6:7], v[158:159], v[8:9]
	s_nop 0
	v_cvt_pk_bf16_f32 v5, v6, v7
	s_nop 0
	v_pk_mul_f32 v[6:7], v[10:11], v[160:161]
	v_pk_mul_f32 v[10:11], v[72:73], v[16:17] op_sel_hi:[1,0]
	v_cvt_pk_bf16_f32 v6, v6, v7
	v_pk_mul_f32 v[8:9], v[10:11], v[162:163]
	s_nop 0
	v_permlane32_swap_b32_e32 v4, v6
	v_cvt_pk_bf16_f32 v7, v8, v9
	s_nop 1
	v_permlane32_swap_b32_e32 v5, v7
	global_store_dwordx4 v[0:1], v[4:7], off offset:32
	s_nop 0
	v_pk_mul_f32 v[8:9], v[78:79], v[16:17] op_sel_hi:[1,0]
	v_pk_mul_f32 v[10:11], v[70:71], v[16:17] op_sel_hi:[1,0]
	s_nop 0
	v_pk_mul_f32 v[4:5], v[8:9], v[164:165]
	v_pk_mul_f32 v[8:9], v[76:77], v[16:17] op_sel_hi:[1,0]
	v_cvt_pk_bf16_f32 v4, v4, v5
	v_pk_mul_f32 v[6:7], v[8:9], v[166:167]
	s_nop 0
	v_cvt_pk_bf16_f32 v5, v6, v7
	s_nop 0
	v_pk_mul_f32 v[6:7], v[10:11], v[168:169]
	v_pk_mul_f32 v[10:11], v[68:69], v[16:17] op_sel_hi:[1,0]
	v_cvt_pk_bf16_f32 v6, v6, v7
	v_pk_mul_f32 v[8:9], v[10:11], v[170:171]
	s_nop 0
	v_permlane32_swap_b32_e32 v4, v6
	v_cvt_pk_bf16_f32 v7, v8, v9
	s_nop 1
	v_permlane32_swap_b32_e32 v5, v7
	global_store_dwordx4 v[0:1], v[4:7], off offset:64
	s_nop 0
	v_pk_mul_f32 v[8:9], v[60:61], v[16:17] op_sel_hi:[1,0]
	v_pk_mul_f32 v[10:11], v[64:65], v[16:17] op_sel_hi:[1,0]
	s_nop 0
	v_pk_mul_f32 v[4:5], v[8:9], v[172:173]
	v_pk_mul_f32 v[8:9], v[62:63], v[16:17] op_sel_hi:[1,0]
	v_cvt_pk_bf16_f32 v4, v4, v5
	v_pk_mul_f32 v[6:7], v[8:9], v[174:175]
	s_nop 0
	v_cvt_pk_bf16_f32 v5, v6, v7
	s_nop 0
	v_pk_mul_f32 v[6:7], v[10:11], v[176:177]
	v_pk_mul_f32 v[10:11], v[54:55], v[16:17] op_sel_hi:[1,0]
	v_cvt_pk_bf16_f32 v6, v6, v7
	v_pk_mul_f32 v[8:9], v[10:11], v[178:179]
	s_nop 0
	v_permlane32_swap_b32_e32 v4, v6
	v_cvt_pk_bf16_f32 v7, v8, v9
	s_nop 1
	v_permlane32_swap_b32_e32 v5, v7
	global_store_dwordx4 v[0:1], v[4:7], off offset:96
	s_nop 0
	v_pk_mul_f32 v[8:9], v[58:59], v[16:17] op_sel_hi:[1,0]
	v_pk_mul_f32 v[10:11], v[52:53], v[16:17] op_sel_hi:[1,0]
	s_nop 0
	v_pk_mul_f32 v[4:5], v[8:9], v[180:181]
	v_pk_mul_f32 v[8:9], v[56:57], v[16:17] op_sel_hi:[1,0]
	v_cvt_pk_bf16_f32 v4, v4, v5
	v_pk_mul_f32 v[6:7], v[8:9], v[182:183]
	s_nop 0
	v_cvt_pk_bf16_f32 v5, v6, v7
	s_nop 0
	v_pk_mul_f32 v[6:7], v[10:11], v[184:185]
	v_pk_mul_f32 v[10:11], v[42:43], v[16:17] op_sel_hi:[1,0]
	v_cvt_pk_bf16_f32 v6, v6, v7
	v_pk_mul_f32 v[8:9], v[10:11], v[186:187]
	s_nop 0
	v_permlane32_swap_b32_e32 v4, v6
	v_cvt_pk_bf16_f32 v7, v8, v9
	s_nop 1
	v_permlane32_swap_b32_e32 v5, v7
	global_store_dwordx4 v[0:1], v[4:7], off offset:128
	s_nop 0
	v_pk_mul_f32 v[8:9], v[44:45], v[16:17] op_sel_hi:[1,0]
	v_pk_mul_f32 v[10:11], v[38:39], v[16:17] op_sel_hi:[1,0]
	s_nop 0
	v_pk_mul_f32 v[4:5], v[8:9], v[208:209]
	v_pk_mul_f32 v[8:9], v[40:41], v[16:17] op_sel_hi:[1,0]
	v_cvt_pk_bf16_f32 v4, v4, v5
	v_pk_mul_f32 v[6:7], v[8:9], v[210:211]
	s_nop 0
	v_cvt_pk_bf16_f32 v5, v6, v7
	s_nop 0
	v_pk_mul_f32 v[6:7], v[10:11], v[220:221]
	v_pk_mul_f32 v[10:11], v[34:35], v[16:17] op_sel_hi:[1,0]
	v_cvt_pk_bf16_f32 v6, v6, v7
	v_pk_mul_f32 v[8:9], v[10:11], v[222:223]
	s_nop 0
	v_permlane32_swap_b32_e32 v4, v6
	v_cvt_pk_bf16_f32 v7, v8, v9
	s_nop 1
	v_permlane32_swap_b32_e32 v5, v7
	global_store_dwordx4 v[0:1], v[4:7], off offset:160
	s_nop 0
	v_pk_mul_f32 v[8:9], v[36:37], v[16:17] op_sel_hi:[1,0]
	v_pk_mul_f32 v[10:11], v[24:25], v[16:17] op_sel_hi:[1,0]
	s_nop 0
	v_pk_mul_f32 v[4:5], v[8:9], v[224:225]
	v_pk_mul_f32 v[8:9], v[26:27], v[16:17] op_sel_hi:[1,0]
	v_cvt_pk_bf16_f32 v4, v4, v5
	v_pk_mul_f32 v[6:7], v[8:9], v[226:227]
	s_nop 0
	v_cvt_pk_bf16_f32 v5, v6, v7
	s_nop 0
	v_pk_mul_f32 v[6:7], v[10:11], v[228:229]
	v_pk_mul_f32 v[10:11], v[18:19], v[16:17] op_sel_hi:[1,0]
	v_cvt_pk_bf16_f32 v6, v6, v7
	v_pk_mul_f32 v[8:9], v[10:11], v[230:231]
	s_nop 0
	v_permlane32_swap_b32_e32 v4, v6
	v_cvt_pk_bf16_f32 v7, v8, v9
	s_nop 1
	v_permlane32_swap_b32_e32 v5, v7
	global_store_dwordx4 v[0:1], v[4:7], off offset:192
	s_nop 0
	v_pk_mul_f32 v[8:9], v[22:23], v[16:17] op_sel_hi:[1,0]
	v_pk_mul_f32 v[10:11], v[14:15], v[16:17] op_sel_hi:[1,0]
	s_nop 0
	v_pk_mul_f32 v[4:5], v[8:9], v[232:233]
	v_pk_mul_f32 v[8:9], v[20:21], v[16:17] op_sel_hi:[1,0]
	v_cvt_pk_bf16_f32 v4, v4, v5
	v_pk_mul_f32 v[6:7], v[8:9], v[234:235]
	s_nop 0
	v_cvt_pk_bf16_f32 v5, v6, v7
	s_nop 0
	v_pk_mul_f32 v[6:7], v[10:11], v[190:191]
	v_pk_mul_f32 v[10:11], v[12:13], v[16:17] op_sel_hi:[1,0]
	v_cvt_pk_bf16_f32 v6, v6, v7
	v_pk_mul_f32 v[8:9], v[10:11], v[192:193]
	s_nop 0
	v_permlane32_swap_b32_e32 v4, v6
	v_cvt_pk_bf16_f32 v7, v8, v9
	s_nop 1
	v_permlane32_swap_b32_e32 v5, v7
	global_store_dwordx4 v[0:1], v[4:7], off offset:224
	s_branch .LBB0_317
